# v45: v41 + the redundant s_waitcnt lgkmcnt(0) between each barrier and the first MFMA of a segment removed (five K-loops, 20 sites)
# baseline (speedup 1.0000x reference)
.LBB0_230:
	s_add_u32 s98, s0, 0xfff00000
	s_addc_u32 s99, s1, -1
	s_add_u32 s28, s0, 0xfff00080
	s_addc_u32 s29, s1, -1
	s_add_i32 s51, 0, 0x10000
	s_cmp_eq_u32 s50, 60
	s_cselect_b32 s31, s34, s29
	s_cselect_b32 s30, s35, s28
	v_add_u32_e32 v0, s51, v179
	s_cselect_b32 s29, s27, s43
	s_cselect_b32 s28, s40, s41
	s_add_i32 s77, 0, 0x14000
	ds_read_b128 v[130:133], v0
	ds_read_b128 v[134:137], v0 offset:1024
	ds_read_b128 v[138:141], v0 offset:2048
	ds_read_b128 v[142:145], v0 offset:3072
	v_add_u32_e32 v0, s77, v179
	ds_read_b128 v[146:149], v0
	ds_read_b128 v[150:153], v0 offset:1024
	ds_read_b128 v[154:157], v0 offset:2048
	ds_read_b128 v[158:161], v0 offset:3072
	s_mov_b32 m0, s54
	ds_read_b128 v[174:177], v192
	ds_read_b128 v[180:183], v192 offset:1024
	ds_read_b128 v[184:187], v192 offset:2048
	ds_read_b128 v[188:191], v192 offset:3072
	ds_read_b128 v[200:203], v192 offset:4096
	ds_read_b128 v[204:207], v192 offset:5120
	ds_read_b128 v[208:211], v192 offset:6144
	ds_read_b128 v[212:215], v192 offset:7168
	global_load_lds_dwordx4 v168, s[98:99]
	s_mov_b32 m0, s55
	s_nop 0
	global_load_lds_dwordx4 v164, s[98:99]
	s_add_i32 m0, s14, 0xc000
	s_nop 0
	global_load_lds_dwordx4 v170, s[0:1]
	s_add_i32 m0, s14, 0xe000
	s_nop 0
	global_load_lds_dwordx4 v172, s[0:1]
	s_waitcnt vmcnt(8)
	s_waitcnt lgkmcnt(0)
	s_barrier
	v_mfma_f32_16x16x32_bf16 v[126:129], v[130:133], v[174:177], v[126:129]
	v_mfma_f32_16x16x32_bf16 v[126:129], v[134:137], v[180:183], v[126:129]
	v_mfma_f32_16x16x32_bf16 v[110:113], v[130:133], v[184:187], v[110:113]
	v_mfma_f32_16x16x32_bf16 v[110:113], v[134:137], v[188:191], v[110:113]
	v_mfma_f32_16x16x32_bf16 v[94:97], v[130:133], v[200:203], v[94:97]
	v_mfma_f32_16x16x32_bf16 v[94:97], v[134:137], v[204:207], v[94:97]
	v_mfma_f32_16x16x32_bf16 v[78:81], v[130:133], v[208:211], v[78:81]
	v_mfma_f32_16x16x32_bf16 v[78:81], v[134:137], v[212:215], v[78:81]
	v_mfma_f32_16x16x32_bf16 v[122:125], v[138:141], v[174:177], v[122:125]
	v_mfma_f32_16x16x32_bf16 v[122:125], v[142:145], v[180:183], v[122:125]
	v_mfma_f32_16x16x32_bf16 v[106:109], v[138:141], v[184:187], v[106:109]
	v_mfma_f32_16x16x32_bf16 v[106:109], v[142:145], v[188:191], v[106:109]
	v_mfma_f32_16x16x32_bf16 v[90:93], v[138:141], v[200:203], v[90:93]
	v_mfma_f32_16x16x32_bf16 v[90:93], v[142:145], v[204:207], v[90:93]
	v_mfma_f32_16x16x32_bf16 v[74:77], v[138:141], v[208:211], v[74:77]
	v_mfma_f32_16x16x32_bf16 v[74:77], v[142:145], v[212:215], v[74:77]
	v_mfma_f32_16x16x32_bf16 v[118:121], v[146:149], v[174:177], v[118:121]
	v_mfma_f32_16x16x32_bf16 v[118:121], v[150:153], v[180:183], v[118:121]
	v_mfma_f32_16x16x32_bf16 v[102:105], v[146:149], v[184:187], v[102:105]
	v_mfma_f32_16x16x32_bf16 v[102:105], v[150:153], v[188:191], v[102:105]
	v_mfma_f32_16x16x32_bf16 v[86:89], v[146:149], v[200:203], v[86:89]
	v_mfma_f32_16x16x32_bf16 v[86:89], v[150:153], v[204:207], v[86:89]
	v_mfma_f32_16x16x32_bf16 v[70:73], v[146:149], v[208:211], v[70:73]
	v_mfma_f32_16x16x32_bf16 v[70:73], v[150:153], v[212:215], v[70:73]
	v_mfma_f32_16x16x32_bf16 v[114:117], v[154:157], v[174:177], v[114:117]
	v_mfma_f32_16x16x32_bf16 v[114:117], v[158:161], v[180:183], v[114:117]
	v_mfma_f32_16x16x32_bf16 v[98:101], v[154:157], v[184:187], v[98:101]
	v_mfma_f32_16x16x32_bf16 v[98:101], v[158:161], v[188:191], v[98:101]
	v_mfma_f32_16x16x32_bf16 v[82:85], v[154:157], v[200:203], v[82:85]
	v_mfma_f32_16x16x32_bf16 v[82:85], v[158:161], v[204:207], v[82:85]
	v_mfma_f32_16x16x32_bf16 v[66:69], v[154:157], v[208:211], v[66:69]
	v_mfma_f32_16x16x32_bf16 v[66:69], v[158:161], v[212:215], v[66:69]
	s_barrier
	s_add_i32 s51, s51, s9
	s_mov_b32 m0, s51
	ds_read_b128 v[174:177], v192 offset:16384
	ds_read_b128 v[180:183], v192 offset:17408
	ds_read_b128 v[184:187], v192 offset:18432
	ds_read_b128 v[188:191], v192 offset:19456
	ds_read_b128 v[200:203], v192 offset:20480
	ds_read_b128 v[204:207], v192 offset:21504
	ds_read_b128 v[208:211], v192 offset:22528
	ds_read_b128 v[212:215], v192 offset:23552
	global_load_lds_dwordx4 v166, s[28:29]
	s_add_i32 m0, s51, 0x2000
	s_add_u32 s80, s28, 0x100000
	s_addc_u32 s81, s29, 0
	s_add_i32 s51, s77, s9
	global_load_lds_dwordx4 v162, s[28:29]
	s_mov_b32 m0, s51
	s_nop 0
	global_load_lds_dwordx4 v166, s[80:81]
	s_add_i32 m0, s51, 0x2000
	s_nop 0
	global_load_lds_dwordx4 v162, s[80:81]
	s_waitcnt vmcnt(6)
	s_waitcnt lgkmcnt(0)
	s_barrier
	v_mfma_f32_16x16x32_bf16 v[62:65], v[130:133], v[174:177], v[62:65]
	v_mfma_f32_16x16x32_bf16 v[62:65], v[134:137], v[180:183], v[62:65]
	v_mfma_f32_16x16x32_bf16 v[46:49], v[130:133], v[184:187], v[46:49]
	v_mfma_f32_16x16x32_bf16 v[46:49], v[134:137], v[188:191], v[46:49]
	v_mfma_f32_16x16x32_bf16 v[30:33], v[130:133], v[200:203], v[30:33]
	v_mfma_f32_16x16x32_bf16 v[30:33], v[134:137], v[204:207], v[30:33]
	v_mfma_f32_16x16x32_bf16 v[14:17], v[130:133], v[208:211], v[14:17]
	v_mfma_f32_16x16x32_bf16 v[14:17], v[134:137], v[212:215], v[14:17]
	v_mfma_f32_16x16x32_bf16 v[58:61], v[138:141], v[174:177], v[58:61]
	v_mfma_f32_16x16x32_bf16 v[58:61], v[142:145], v[180:183], v[58:61]
	v_mfma_f32_16x16x32_bf16 v[42:45], v[138:141], v[184:187], v[42:45]
	v_mfma_f32_16x16x32_bf16 v[42:45], v[142:145], v[188:191], v[42:45]
	v_mfma_f32_16x16x32_bf16 v[26:29], v[138:141], v[200:203], v[26:29]
	v_mfma_f32_16x16x32_bf16 v[26:29], v[142:145], v[204:207], v[26:29]
	v_mfma_f32_16x16x32_bf16 v[10:13], v[138:141], v[208:211], v[10:13]
	v_mfma_f32_16x16x32_bf16 v[10:13], v[142:145], v[212:215], v[10:13]
	v_mfma_f32_16x16x32_bf16 v[54:57], v[146:149], v[174:177], v[54:57]
	v_mfma_f32_16x16x32_bf16 v[54:57], v[150:153], v[180:183], v[54:57]
	v_mfma_f32_16x16x32_bf16 v[38:41], v[146:149], v[184:187], v[38:41]
	v_mfma_f32_16x16x32_bf16 v[38:41], v[150:153], v[188:191], v[38:41]
	v_mfma_f32_16x16x32_bf16 v[22:25], v[146:149], v[200:203], v[22:25]
	v_mfma_f32_16x16x32_bf16 v[22:25], v[150:153], v[204:207], v[22:25]
	v_mfma_f32_16x16x32_bf16 v[6:9], v[146:149], v[208:211], v[6:9]
	v_mfma_f32_16x16x32_bf16 v[6:9], v[150:153], v[212:215], v[6:9]
	v_mfma_f32_16x16x32_bf16 v[50:53], v[154:157], v[174:177], v[50:53]
	v_mfma_f32_16x16x32_bf16 v[50:53], v[158:161], v[180:183], v[50:53]
	v_mfma_f32_16x16x32_bf16 v[34:37], v[154:157], v[184:187], v[34:37]
	v_mfma_f32_16x16x32_bf16 v[34:37], v[158:161], v[188:191], v[34:37]
	v_mfma_f32_16x16x32_bf16 v[18:21], v[154:157], v[200:203], v[18:21]
	v_mfma_f32_16x16x32_bf16 v[18:21], v[158:161], v[204:207], v[18:21]
	v_mfma_f32_16x16x32_bf16 v[2:5], v[154:157], v[208:211], v[2:5]
	v_mfma_f32_16x16x32_bf16 v[2:5], v[158:161], v[212:215], v[2:5]
	s_barrier
	s_add_i32 s51, 0, 0x18000
	v_add_u32_e32 v0, s51, v179
	s_add_i32 s77, 0, 0x1c000
	ds_read_b128 v[130:133], v0
	ds_read_b128 v[134:137], v0 offset:1024
	ds_read_b128 v[138:141], v0 offset:2048
	ds_read_b128 v[142:145], v0 offset:3072
	v_add_u32_e32 v0, s77, v179
	ds_read_b128 v[146:149], v0
	ds_read_b128 v[150:153], v0 offset:1024
	ds_read_b128 v[154:157], v0 offset:2048
	ds_read_b128 v[158:161], v0 offset:3072
	s_mov_b32 m0, s14
	ds_read_b128 v[174:177], v192 offset:32768
	ds_read_b128 v[180:183], v192 offset:33792
	ds_read_b128 v[184:187], v192 offset:34816
	ds_read_b128 v[188:191], v192 offset:35840
	ds_read_b128 v[200:203], v192 offset:36864
	ds_read_b128 v[204:207], v192 offset:37888
	ds_read_b128 v[208:211], v192 offset:38912
	ds_read_b128 v[212:215], v192 offset:39936
	global_load_lds_dwordx4 v168, s[30:31]
	s_mov_b32 m0, s15
	s_nop 0
	global_load_lds_dwordx4 v164, s[30:31]
	s_add_u32 s30, s30, 0x100000
	s_addc_u32 s31, s31, 0
	s_mov_b32 m0, s52
	s_nop 0
	global_load_lds_dwordx4 v168, s[30:31]
	s_mov_b32 m0, s53
	s_nop 0
	global_load_lds_dwordx4 v164, s[30:31]
	s_waitcnt vmcnt(8)
	s_waitcnt lgkmcnt(0)
	s_barrier
	v_mfma_f32_16x16x32_bf16 v[126:129], v[130:133], v[174:177], v[126:129]
	v_mfma_f32_16x16x32_bf16 v[126:129], v[134:137], v[180:183], v[126:129]
	v_mfma_f32_16x16x32_bf16 v[110:113], v[130:133], v[184:187], v[110:113]
	v_mfma_f32_16x16x32_bf16 v[110:113], v[134:137], v[188:191], v[110:113]
	v_mfma_f32_16x16x32_bf16 v[94:97], v[130:133], v[200:203], v[94:97]
	v_mfma_f32_16x16x32_bf16 v[94:97], v[134:137], v[204:207], v[94:97]
	v_mfma_f32_16x16x32_bf16 v[78:81], v[130:133], v[208:211], v[78:81]
	v_mfma_f32_16x16x32_bf16 v[78:81], v[134:137], v[212:215], v[78:81]
	v_mfma_f32_16x16x32_bf16 v[122:125], v[138:141], v[174:177], v[122:125]
	v_mfma_f32_16x16x32_bf16 v[122:125], v[142:145], v[180:183], v[122:125]
	v_mfma_f32_16x16x32_bf16 v[106:109], v[138:141], v[184:187], v[106:109]
	v_mfma_f32_16x16x32_bf16 v[106:109], v[142:145], v[188:191], v[106:109]
	v_mfma_f32_16x16x32_bf16 v[90:93], v[138:141], v[200:203], v[90:93]
	v_mfma_f32_16x16x32_bf16 v[90:93], v[142:145], v[204:207], v[90:93]
	v_mfma_f32_16x16x32_bf16 v[74:77], v[138:141], v[208:211], v[74:77]
	v_mfma_f32_16x16x32_bf16 v[74:77], v[142:145], v[212:215], v[74:77]
	v_mfma_f32_16x16x32_bf16 v[118:121], v[146:149], v[174:177], v[118:121]
	v_mfma_f32_16x16x32_bf16 v[118:121], v[150:153], v[180:183], v[118:121]
	v_mfma_f32_16x16x32_bf16 v[102:105], v[146:149], v[184:187], v[102:105]
	v_mfma_f32_16x16x32_bf16 v[102:105], v[150:153], v[188:191], v[102:105]
	v_mfma_f32_16x16x32_bf16 v[86:89], v[146:149], v[200:203], v[86:89]
	v_mfma_f32_16x16x32_bf16 v[86:89], v[150:153], v[204:207], v[86:89]
	v_mfma_f32_16x16x32_bf16 v[70:73], v[146:149], v[208:211], v[70:73]
	v_mfma_f32_16x16x32_bf16 v[70:73], v[150:153], v[212:215], v[70:73]
	v_mfma_f32_16x16x32_bf16 v[114:117], v[154:157], v[174:177], v[114:117]
	v_mfma_f32_16x16x32_bf16 v[114:117], v[158:161], v[180:183], v[114:117]
	v_mfma_f32_16x16x32_bf16 v[98:101], v[154:157], v[184:187], v[98:101]
	v_mfma_f32_16x16x32_bf16 v[98:101], v[158:161], v[188:191], v[98:101]
	v_mfma_f32_16x16x32_bf16 v[82:85], v[154:157], v[200:203], v[82:85]
	v_mfma_f32_16x16x32_bf16 v[82:85], v[158:161], v[204:207], v[82:85]
	v_mfma_f32_16x16x32_bf16 v[66:69], v[154:157], v[208:211], v[66:69]
	v_mfma_f32_16x16x32_bf16 v[66:69], v[158:161], v[212:215], v[66:69]
	s_barrier
	s_add_u32 s98, s28, 0x80
	s_addc_u32 s99, s29, 0
	s_add_i32 s30, s51, s9
	s_mov_b32 m0, s30
	ds_read_b128 v[174:177], v192 offset:49152
	ds_read_b128 v[180:183], v192 offset:50176
	ds_read_b128 v[184:187], v192 offset:51200
	ds_read_b128 v[188:191], v192 offset:52224
	ds_read_b128 v[200:203], v192 offset:53248
	ds_read_b128 v[204:207], v192 offset:54272
	ds_read_b128 v[208:211], v192 offset:55296
	ds_read_b128 v[212:215], v192 offset:56320
	global_load_lds_dwordx4 v166, s[98:99]
	s_add_i32 m0, s30, 0x2000
	s_add_u32 s28, s28, 0x100080
	s_addc_u32 s29, s29, 0
	s_add_i32 s30, s77, s9
	global_load_lds_dwordx4 v162, s[98:99]
	s_mov_b32 m0, s30
	s_nop 0
	global_load_lds_dwordx4 v166, s[28:29]
	s_add_i32 m0, s30, 0x2000
	s_nop 0
	global_load_lds_dwordx4 v162, s[28:29]
	s_waitcnt vmcnt(6)
	s_waitcnt lgkmcnt(0)
	s_barrier
	v_mfma_f32_16x16x32_bf16 v[62:65], v[130:133], v[174:177], v[62:65]
	v_mfma_f32_16x16x32_bf16 v[62:65], v[134:137], v[180:183], v[62:65]
	v_mfma_f32_16x16x32_bf16 v[46:49], v[130:133], v[184:187], v[46:49]
	v_mfma_f32_16x16x32_bf16 v[46:49], v[134:137], v[188:191], v[46:49]
	v_mfma_f32_16x16x32_bf16 v[30:33], v[130:133], v[200:203], v[30:33]
	v_mfma_f32_16x16x32_bf16 v[30:33], v[134:137], v[204:207], v[30:33]
	v_mfma_f32_16x16x32_bf16 v[14:17], v[130:133], v[208:211], v[14:17]
	v_mfma_f32_16x16x32_bf16 v[14:17], v[134:137], v[212:215], v[14:17]
	v_mfma_f32_16x16x32_bf16 v[58:61], v[138:141], v[174:177], v[58:61]
	v_mfma_f32_16x16x32_bf16 v[58:61], v[142:145], v[180:183], v[58:61]
	v_mfma_f32_16x16x32_bf16 v[42:45], v[138:141], v[184:187], v[42:45]
	v_mfma_f32_16x16x32_bf16 v[42:45], v[142:145], v[188:191], v[42:45]
	v_mfma_f32_16x16x32_bf16 v[26:29], v[138:141], v[200:203], v[26:29]
	v_mfma_f32_16x16x32_bf16 v[26:29], v[142:145], v[204:207], v[26:29]
	v_mfma_f32_16x16x32_bf16 v[10:13], v[138:141], v[208:211], v[10:13]
	v_mfma_f32_16x16x32_bf16 v[10:13], v[142:145], v[212:215], v[10:13]
	v_mfma_f32_16x16x32_bf16 v[54:57], v[146:149], v[174:177], v[54:57]
	v_mfma_f32_16x16x32_bf16 v[54:57], v[150:153], v[180:183], v[54:57]
	v_mfma_f32_16x16x32_bf16 v[38:41], v[146:149], v[184:187], v[38:41]
	v_mfma_f32_16x16x32_bf16 v[38:41], v[150:153], v[188:191], v[38:41]
	v_mfma_f32_16x16x32_bf16 v[22:25], v[146:149], v[200:203], v[22:25]
	v_mfma_f32_16x16x32_bf16 v[22:25], v[150:153], v[204:207], v[22:25]
	v_mfma_f32_16x16x32_bf16 v[6:9], v[146:149], v[208:211], v[6:9]
	v_mfma_f32_16x16x32_bf16 v[6:9], v[150:153], v[212:215], v[6:9]
	v_mfma_f32_16x16x32_bf16 v[50:53], v[154:157], v[174:177], v[50:53]
	v_mfma_f32_16x16x32_bf16 v[50:53], v[158:161], v[180:183], v[50:53]
	v_mfma_f32_16x16x32_bf16 v[34:37], v[154:157], v[184:187], v[34:37]
	v_mfma_f32_16x16x32_bf16 v[34:37], v[158:161], v[188:191], v[34:37]
	v_mfma_f32_16x16x32_bf16 v[18:21], v[154:157], v[200:203], v[18:21]
	v_mfma_f32_16x16x32_bf16 v[18:21], v[158:161], v[204:207], v[18:21]
	v_mfma_f32_16x16x32_bf16 v[2:5], v[154:157], v[208:211], v[2:5]
	v_mfma_f32_16x16x32_bf16 v[2:5], v[158:161], v[212:215], v[2:5]
	s_barrier
	s_add_i32 s50, s50, 2
	s_add_u32 s0, s0, 0x100
	s_addc_u32 s1, s1, 0
	s_add_u32 s41, s41, 0x100
	s_addc_u32 s43, s43, 0
	s_cmp_gt_u32 s50, 61
	s_cbranch_scc0 .LBB0_230
	s_and_b64 vcc, exec, s[22:23]
	s_cbranch_vccz .LBB0_233
	s_barrier

.Lspf_j0:
	s_waitcnt lgkmcnt(0)
	s_barrier
	v_mfma_i32_16x16x64_i8 v[142:145], v[2:5], v[174:177], v[142:145]
	v_mfma_i32_16x16x64_i8 v[142:145], v[6:9], v[178:181], v[142:145]
	v_mfma_i32_16x16x64_i8 v[134:137], v[2:5], v[182:185], v[134:137]
	v_mfma_i32_16x16x64_i8 v[134:137], v[6:9], v[186:189], v[134:137]
	v_mfma_i32_16x16x64_i8 v[122:125], v[2:5], v[190:193], v[122:125]
	v_mfma_i32_16x16x64_i8 v[122:125], v[6:9], v[200:203], v[122:125]
	v_mfma_i32_16x16x64_i8 v[106:109], v[2:5], v[204:207], v[106:109]
	v_mfma_i32_16x16x64_i8 v[106:109], v[6:9], v[208:211], v[106:109]
	v_mfma_i32_16x16x64_i8 v[138:141], v[10:13], v[174:177], v[138:141]
	v_mfma_i32_16x16x64_i8 v[138:141], v[14:17], v[178:181], v[138:141]
	v_mfma_i32_16x16x64_i8 v[130:133], v[10:13], v[182:185], v[130:133]
	v_mfma_i32_16x16x64_i8 v[130:133], v[14:17], v[186:189], v[130:133]
	v_mfma_i32_16x16x64_i8 v[114:117], v[10:13], v[190:193], v[114:117]
	v_mfma_i32_16x16x64_i8 v[114:117], v[14:17], v[200:203], v[114:117]
	v_mfma_i32_16x16x64_i8 v[98:101], v[10:13], v[204:207], v[98:101]
	v_mfma_i32_16x16x64_i8 v[98:101], v[14:17], v[208:211], v[98:101]
	v_mfma_i32_16x16x64_i8 v[126:129], v[146:149], v[174:177], v[126:129]
	v_mfma_i32_16x16x64_i8 v[126:129], v[150:153], v[178:181], v[126:129]
	v_mfma_i32_16x16x64_i8 v[110:113], v[146:149], v[182:185], v[110:113]
	v_mfma_i32_16x16x64_i8 v[110:113], v[150:153], v[186:189], v[110:113]
	v_mfma_i32_16x16x64_i8 v[94:97], v[146:149], v[190:193], v[94:97]
	v_mfma_i32_16x16x64_i8 v[94:97], v[150:153], v[200:203], v[94:97]
	v_mfma_i32_16x16x64_i8 v[86:89], v[146:149], v[204:207], v[86:89]
	v_mfma_i32_16x16x64_i8 v[86:89], v[150:153], v[208:211], v[86:89]
	v_mfma_i32_16x16x64_i8 v[118:121], v[154:157], v[174:177], v[118:121]
	v_mfma_i32_16x16x64_i8 v[118:121], v[158:161], v[178:181], v[118:121]
	v_mfma_i32_16x16x64_i8 v[102:105], v[154:157], v[182:185], v[102:105]
	v_mfma_i32_16x16x64_i8 v[102:105], v[158:161], v[186:189], v[102:105]
	v_mfma_i32_16x16x64_i8 v[90:93], v[154:157], v[190:193], v[90:93]
	v_mfma_i32_16x16x64_i8 v[90:93], v[158:161], v[200:203], v[90:93]
	v_mfma_i32_16x16x64_i8 v[82:85], v[154:157], v[204:207], v[82:85]
	v_mfma_i32_16x16x64_i8 v[82:85], v[158:161], v[208:211], v[82:85]
	s_barrier
	s_add_i32 s42, s42, s81
	s_mov_b32 m0, s42
	ds_read_b128 v[174:177], v250 offset:16384
	ds_read_b128 v[178:181], v250 offset:17408
	ds_read_b128 v[182:185], v250 offset:18432
	ds_read_b128 v[186:189], v250 offset:19456
	ds_read_b128 v[190:193], v250 offset:20480
	ds_read_b128 v[200:203], v250 offset:21504
	ds_read_b128 v[204:207], v250 offset:22528
	ds_read_b128 v[208:211], v250 offset:23552
	global_load_lds_dwordx4 v164, s[28:29]
	s_add_i32 m0, s42, 0x2000
	s_add_u32 s42, s28, 0x80000
	s_addc_u32 s43, s29, 0
	s_add_i32 s49, s49, s81
	global_load_lds_dwordx4 v168, s[28:29]
	s_mov_b32 m0, s49
	s_nop 0
	global_load_lds_dwordx4 v164, s[42:43]
	s_add_i32 m0, s49, 0x2000
	s_nop 0
	global_load_lds_dwordx4 v168, s[42:43]
	s_cmp_eq_u32 s41, 28
	s_cbranch_scc1 .Lspf_w1
	s_waitcnt vmcnt(6)
	s_branch .Lspf_j1

.Lspf_j1:
	s_waitcnt lgkmcnt(0)
	s_barrier
	v_mfma_i32_16x16x64_i8 v[78:81], v[2:5], v[174:177], v[78:81]
	v_mfma_i32_16x16x64_i8 v[78:81], v[6:9], v[178:181], v[78:81]
	v_mfma_i32_16x16x64_i8 v[74:77], v[10:13], v[174:177], v[74:77]
	v_mfma_i32_16x16x64_i8 v[74:77], v[14:17], v[178:181], v[74:77]
	v_mfma_i32_16x16x64_i8 v[70:73], v[2:5], v[182:185], v[70:73]
	v_mfma_i32_16x16x64_i8 v[70:73], v[6:9], v[186:189], v[70:73]
	v_mfma_i32_16x16x64_i8 v[66:69], v[10:13], v[182:185], v[66:69]
	v_mfma_i32_16x16x64_i8 v[66:69], v[14:17], v[186:189], v[66:69]
	v_mfma_i32_16x16x64_i8 v[54:57], v[2:5], v[190:193], v[54:57]
	v_mfma_i32_16x16x64_i8 v[54:57], v[6:9], v[200:203], v[54:57]
	v_mfma_i32_16x16x64_i8 v[50:53], v[10:13], v[190:193], v[50:53]
	v_mfma_i32_16x16x64_i8 v[50:53], v[14:17], v[200:203], v[50:53]
	v_mfma_i32_16x16x64_i8 v[2:5], v[2:5], v[204:207], v[38:41]
	v_mfma_i32_16x16x64_i8 v[2:5], v[6:9], v[208:211], v[2:5]
	v_mfma_i32_16x16x64_i8 v[6:9], v[10:13], v[204:207], v[34:37]
	v_mfma_i32_16x16x64_i8 v[6:9], v[14:17], v[208:211], v[6:9]
	v_mfma_i32_16x16x64_i8 v[34:37], v[146:149], v[182:185], v[46:49]
	v_mfma_i32_16x16x64_i8 v[46:49], v[150:153], v[186:189], v[34:37]
	v_mfma_i32_16x16x64_i8 v[34:37], v[154:157], v[182:185], v[42:45]
	v_mfma_i32_16x16x64_i8 v[42:45], v[158:161], v[186:189], v[34:37]
	v_mfma_i32_16x16x64_i8 v[30:33], v[146:149], v[190:193], v[30:33]
	v_mfma_i32_16x16x64_i8 v[30:33], v[150:153], v[200:203], v[30:33]
	v_mfma_i32_16x16x64_i8 v[26:29], v[154:157], v[190:193], v[26:29]
	v_mfma_i32_16x16x64_i8 v[26:29], v[158:161], v[200:203], v[26:29]
	v_mfma_i32_16x16x64_i8 v[22:25], v[146:149], v[204:207], v[22:25]
	v_mfma_i32_16x16x64_i8 v[22:25], v[150:153], v[208:211], v[22:25]
	v_mfma_i32_16x16x64_i8 v[18:21], v[154:157], v[204:207], v[18:21]
	v_mfma_i32_16x16x64_i8 v[18:21], v[158:161], v[208:211], v[18:21]
	v_mfma_i32_16x16x64_i8 v[10:13], v[146:149], v[174:177], v[62:65]
	v_mfma_i32_16x16x64_i8 v[10:13], v[150:153], v[178:181], v[10:13]
	v_mfma_i32_16x16x64_i8 v[14:17], v[154:157], v[174:177], v[58:61]
	v_mfma_i32_16x16x64_i8 v[14:17], v[158:161], v[178:181], v[14:17]
	s_barrier
	s_add_i32 s42, 0, 0x18000
	v_add_u32_e32 v0, s42, v199
	s_add_i32 s43, 0, 0x1c000
	ds_read_b128 v[34:37], v0
	ds_read_b128 v[38:41], v0 offset:1024
	ds_read_b128 v[58:61], v0 offset:2048
	ds_read_b128 v[62:65], v0 offset:3072
	v_add_u32_e32 v0, s43, v199
	ds_read_b128 v[146:149], v0
	ds_read_b128 v[150:153], v0 offset:1024
	ds_read_b128 v[154:157], v0 offset:2048
	ds_read_b128 v[158:161], v0 offset:3072
	s_mov_b32 m0, s21
	ds_read_b128 v[174:177], v250 offset:32768
	ds_read_b128 v[178:181], v250 offset:33792
	ds_read_b128 v[182:185], v250 offset:34816
	ds_read_b128 v[186:189], v250 offset:35840
	ds_read_b128 v[190:193], v250 offset:36864
	ds_read_b128 v[200:203], v250 offset:37888
	ds_read_b128 v[204:207], v250 offset:38912
	ds_read_b128 v[208:211], v250 offset:39936
	global_load_lds_dwordx4 v162, s[30:31]
	s_mov_b32 m0, s57
	s_nop 0
	global_load_lds_dwordx4 v166, s[30:31]
	s_add_u32 s30, s30, 0x80000
	s_addc_u32 s31, s31, 0
	s_mov_b32 m0, s73
	s_nop 0
	global_load_lds_dwordx4 v162, s[30:31]
	s_mov_b32 m0, s76
	s_nop 0
	global_load_lds_dwordx4 v166, s[30:31]
	s_cmp_eq_u32 s41, 28
	s_cbranch_scc1 .Lspf_w2
	s_waitcnt vmcnt(8)
	s_branch .Lspf_j2

.Lspf_j2:
	s_waitcnt lgkmcnt(0)
	s_barrier
	v_mfma_i32_16x16x64_i8 v[142:145], v[34:37], v[174:177], v[142:145]
	v_mfma_i32_16x16x64_i8 v[142:145], v[38:41], v[178:181], v[142:145]
	v_mfma_i32_16x16x64_i8 v[134:137], v[34:37], v[182:185], v[134:137]
	v_mfma_i32_16x16x64_i8 v[134:137], v[38:41], v[186:189], v[134:137]
	v_mfma_i32_16x16x64_i8 v[122:125], v[34:37], v[190:193], v[122:125]
	v_mfma_i32_16x16x64_i8 v[122:125], v[38:41], v[200:203], v[122:125]
	v_mfma_i32_16x16x64_i8 v[106:109], v[34:37], v[204:207], v[106:109]
	v_mfma_i32_16x16x64_i8 v[106:109], v[38:41], v[208:211], v[106:109]
	v_mfma_i32_16x16x64_i8 v[138:141], v[58:61], v[174:177], v[138:141]
	v_mfma_i32_16x16x64_i8 v[138:141], v[62:65], v[178:181], v[138:141]
	v_mfma_i32_16x16x64_i8 v[130:133], v[58:61], v[182:185], v[130:133]
	v_mfma_i32_16x16x64_i8 v[130:133], v[62:65], v[186:189], v[130:133]
	v_mfma_i32_16x16x64_i8 v[114:117], v[58:61], v[190:193], v[114:117]
	v_mfma_i32_16x16x64_i8 v[114:117], v[62:65], v[200:203], v[114:117]
	v_mfma_i32_16x16x64_i8 v[98:101], v[58:61], v[204:207], v[98:101]
	v_mfma_i32_16x16x64_i8 v[98:101], v[62:65], v[208:211], v[98:101]
	v_mfma_i32_16x16x64_i8 v[126:129], v[146:149], v[174:177], v[126:129]
	v_mfma_i32_16x16x64_i8 v[126:129], v[150:153], v[178:181], v[126:129]
	v_mfma_i32_16x16x64_i8 v[110:113], v[146:149], v[182:185], v[110:113]
	v_mfma_i32_16x16x64_i8 v[110:113], v[150:153], v[186:189], v[110:113]
	v_mfma_i32_16x16x64_i8 v[94:97], v[146:149], v[190:193], v[94:97]
	v_mfma_i32_16x16x64_i8 v[94:97], v[150:153], v[200:203], v[94:97]
	v_mfma_i32_16x16x64_i8 v[86:89], v[146:149], v[204:207], v[86:89]
	v_mfma_i32_16x16x64_i8 v[86:89], v[150:153], v[208:211], v[86:89]
	v_mfma_i32_16x16x64_i8 v[118:121], v[154:157], v[174:177], v[118:121]
	v_mfma_i32_16x16x64_i8 v[118:121], v[158:161], v[178:181], v[118:121]
	v_mfma_i32_16x16x64_i8 v[102:105], v[154:157], v[182:185], v[102:105]
	v_mfma_i32_16x16x64_i8 v[102:105], v[158:161], v[186:189], v[102:105]
	v_mfma_i32_16x16x64_i8 v[90:93], v[154:157], v[190:193], v[90:93]
	v_mfma_i32_16x16x64_i8 v[90:93], v[158:161], v[200:203], v[90:93]
	v_mfma_i32_16x16x64_i8 v[82:85], v[154:157], v[204:207], v[82:85]
	v_mfma_i32_16x16x64_i8 v[82:85], v[158:161], v[208:211], v[82:85]
	s_barrier
	s_add_i32 s30, s42, s81
	s_add_u32 s98, s28, 0x80
	s_addc_u32 s99, s29, 0
	s_mov_b32 m0, s30
	ds_read_b128 v[174:177], v250 offset:49152
	ds_read_b128 v[178:181], v250 offset:50176
	ds_read_b128 v[182:185], v250 offset:51200
	ds_read_b128 v[186:189], v250 offset:52224
	ds_read_b128 v[190:193], v250 offset:53248
	ds_read_b128 v[200:203], v250 offset:54272
	ds_read_b128 v[204:207], v250 offset:55296
	ds_read_b128 v[208:211], v250 offset:56320
	global_load_lds_dwordx4 v164, s[98:99]
	s_add_i32 m0, s30, 0x2000
	s_add_u32 s28, s28, 0x80080
	s_addc_u32 s29, s29, 0
	s_add_i32 s30, s43, s81
	global_load_lds_dwordx4 v168, s[98:99]
	s_mov_b32 m0, s30
	s_nop 0
	global_load_lds_dwordx4 v164, s[28:29]
	s_add_i32 m0, s30, 0x2000
	s_nop 0
	global_load_lds_dwordx4 v168, s[28:29]
	s_waitcnt vmcnt(6)
	s_waitcnt lgkmcnt(0)
	s_barrier
	v_mfma_i32_16x16x64_i8 v[78:81], v[34:37], v[174:177], v[78:81]
	v_mfma_i32_16x16x64_i8 v[78:81], v[38:41], v[178:181], v[78:81]
	v_mfma_i32_16x16x64_i8 v[70:73], v[34:37], v[182:185], v[70:73]
	v_mfma_i32_16x16x64_i8 v[70:73], v[38:41], v[186:189], v[70:73]
	v_mfma_i32_16x16x64_i8 v[54:57], v[34:37], v[190:193], v[54:57]
	v_mfma_i32_16x16x64_i8 v[54:57], v[38:41], v[200:203], v[54:57]
	v_mfma_i32_16x16x64_i8 v[2:5], v[34:37], v[204:207], v[2:5]
	v_mfma_i32_16x16x64_i8 v[38:41], v[38:41], v[208:211], v[2:5]
	v_mfma_i32_16x16x64_i8 v[74:77], v[58:61], v[174:177], v[74:77]
	v_mfma_i32_16x16x64_i8 v[74:77], v[62:65], v[178:181], v[74:77]
	v_mfma_i32_16x16x64_i8 v[66:69], v[58:61], v[182:185], v[66:69]
	v_mfma_i32_16x16x64_i8 v[66:69], v[62:65], v[186:189], v[66:69]
	v_mfma_i32_16x16x64_i8 v[50:53], v[58:61], v[190:193], v[50:53]
	v_mfma_i32_16x16x64_i8 v[50:53], v[62:65], v[200:203], v[50:53]
	v_mfma_i32_16x16x64_i8 v[2:5], v[58:61], v[204:207], v[6:9]
	v_mfma_i32_16x16x64_i8 v[34:37], v[62:65], v[208:211], v[2:5]
	v_mfma_i32_16x16x64_i8 v[2:5], v[146:149], v[174:177], v[10:13]
	v_mfma_i32_16x16x64_i8 v[62:65], v[150:153], v[178:181], v[2:5]
	v_mfma_i32_16x16x64_i8 v[2:5], v[154:157], v[174:177], v[14:17]
	v_mfma_i32_16x16x64_i8 v[58:61], v[158:161], v[178:181], v[2:5]
	v_mfma_i32_16x16x64_i8 v[2:5], v[146:149], v[182:185], v[46:49]
	v_mfma_i32_16x16x64_i8 v[46:49], v[150:153], v[186:189], v[2:5]
	v_mfma_i32_16x16x64_i8 v[2:5], v[154:157], v[182:185], v[42:45]
	v_mfma_i32_16x16x64_i8 v[42:45], v[158:161], v[186:189], v[2:5]
	v_mfma_i32_16x16x64_i8 v[2:5], v[146:149], v[190:193], v[30:33]
	v_mfma_i32_16x16x64_i8 v[30:33], v[150:153], v[200:203], v[2:5]
	v_mfma_i32_16x16x64_i8 v[2:5], v[154:157], v[190:193], v[26:29]
	v_mfma_i32_16x16x64_i8 v[26:29], v[158:161], v[200:203], v[2:5]
	v_mfma_i32_16x16x64_i8 v[2:5], v[146:149], v[204:207], v[22:25]
	v_mfma_i32_16x16x64_i8 v[22:25], v[150:153], v[208:211], v[2:5]
	v_mfma_i32_16x16x64_i8 v[2:5], v[154:157], v[204:207], v[18:21]
	v_mfma_i32_16x16x64_i8 v[18:21], v[158:161], v[208:211], v[2:5]
	s_barrier
	s_add_i32 s41, s41, 2
	s_add_u32 s0, s0, 0x100
	s_addc_u32 s1, s1, 0
	s_add_u32 s35, s35, 0x100
	s_addc_u32 s40, s40, 0
	s_cmp_gt_u32 s41, 29
	s_cbranch_scc0 .LBB0_300
	s_and_b64 vcc, exec, s[52:53]
	s_cbranch_vccz .LBB0_303
	s_barrier

.LBB0_577:
	s_add_u32 s98, s30, 0xfff80000
	s_addc_u32 s99, s31, -1
	s_add_u32 s34, s30, 0xfff80080
	s_addc_u32 s35, s31, -1
	s_add_i32 s66, 0, 0x10000
	s_cmp_eq_u32 s57, 28
	s_cselect_b32 s43, s19, s35
	s_cselect_b32 s42, s23, s34
	v_add_u32_e32 v0, s66, v228
	s_cselect_b32 s35, s25, s56
	s_cselect_b32 s34, s54, s55
	s_add_i32 s73, 0, 0x14000
	ds_read_b128 v[132:135], v0
	ds_read_b128 v[136:139], v0 offset:1024
	ds_read_b128 v[140:143], v0 offset:2048
	ds_read_b128 v[144:147], v0 offset:3072
	v_add_u32_e32 v0, s73, v228
	ds_read_b128 v[148:151], v0
	ds_read_b128 v[152:155], v0 offset:1024
	ds_read_b128 v[156:159], v0 offset:2048
	ds_read_b128 v[160:163], v0 offset:3072
	s_mov_b32 m0, s50
	ds_read_b128 v[164:167], v230
	ds_read_b128 v[168:171], v230 offset:1024
	ds_read_b128 v[172:175], v230 offset:2048
	ds_read_b128 v[176:179], v230 offset:3072
	ds_read_b128 v[180:183], v230 offset:4096
	ds_read_b128 v[184:187], v230 offset:5120
	ds_read_b128 v[188:191], v230 offset:6144
	ds_read_b128 v[192:195], v230 offset:7168
	global_load_lds_dwordx4 v206, s[98:99]
	s_mov_b32 m0, s51
	s_nop 0
	global_load_lds_dwordx4 v202, s[98:99]
	s_add_i32 m0, s46, 0xc000
	s_nop 0
	global_load_lds_dwordx4 v208, s[30:31]
	s_add_i32 m0, s46, 0xe000
	s_nop 0
	global_load_lds_dwordx4 v210, s[30:31]
	s_waitcnt vmcnt(8)
	s_waitcnt lgkmcnt(0)
	s_barrier
	v_mfma_f32_16x16x32_bf16 v[128:131], v[132:135], v[164:167], v[128:131]
	v_mfma_f32_16x16x32_bf16 v[128:131], v[136:139], v[168:171], v[128:131]
	v_mfma_f32_16x16x32_bf16 v[120:123], v[132:135], v[172:175], v[120:123]
	v_mfma_f32_16x16x32_bf16 v[120:123], v[136:139], v[176:179], v[120:123]
	v_mfma_f32_16x16x32_bf16 v[112:115], v[132:135], v[180:183], v[112:115]
	v_mfma_f32_16x16x32_bf16 v[112:115], v[136:139], v[184:187], v[112:115]
	v_mfma_f32_16x16x32_bf16 v[104:107], v[132:135], v[188:191], v[104:107]
	v_mfma_f32_16x16x32_bf16 v[104:107], v[136:139], v[192:195], v[104:107]
	v_mfma_f32_16x16x32_bf16 v[124:127], v[140:143], v[164:167], v[124:127]
	v_mfma_f32_16x16x32_bf16 v[124:127], v[144:147], v[168:171], v[124:127]
	v_mfma_f32_16x16x32_bf16 v[116:119], v[140:143], v[172:175], v[116:119]
	v_mfma_f32_16x16x32_bf16 v[116:119], v[144:147], v[176:179], v[116:119]
	v_mfma_f32_16x16x32_bf16 v[108:111], v[140:143], v[180:183], v[108:111]
	v_mfma_f32_16x16x32_bf16 v[108:111], v[144:147], v[184:187], v[108:111]
	v_mfma_f32_16x16x32_bf16 v[100:103], v[140:143], v[188:191], v[100:103]
	v_mfma_f32_16x16x32_bf16 v[100:103], v[144:147], v[192:195], v[100:103]
	v_mfma_f32_16x16x32_bf16 v[96:99], v[148:151], v[164:167], v[96:99]
	v_mfma_f32_16x16x32_bf16 v[96:99], v[152:155], v[168:171], v[96:99]
	v_mfma_f32_16x16x32_bf16 v[88:91], v[148:151], v[172:175], v[88:91]
	v_mfma_f32_16x16x32_bf16 v[88:91], v[152:155], v[176:179], v[88:91]
	v_mfma_f32_16x16x32_bf16 v[80:83], v[148:151], v[180:183], v[80:83]
	v_mfma_f32_16x16x32_bf16 v[80:83], v[152:155], v[184:187], v[80:83]
	v_mfma_f32_16x16x32_bf16 v[72:75], v[148:151], v[188:191], v[72:75]
	v_mfma_f32_16x16x32_bf16 v[72:75], v[152:155], v[192:195], v[72:75]
	v_mfma_f32_16x16x32_bf16 v[92:95], v[156:159], v[164:167], v[92:95]
	v_mfma_f32_16x16x32_bf16 v[92:95], v[160:163], v[168:171], v[92:95]
	v_mfma_f32_16x16x32_bf16 v[84:87], v[156:159], v[172:175], v[84:87]
	v_mfma_f32_16x16x32_bf16 v[84:87], v[160:163], v[176:179], v[84:87]
	v_mfma_f32_16x16x32_bf16 v[76:79], v[156:159], v[180:183], v[76:79]
	v_mfma_f32_16x16x32_bf16 v[76:79], v[160:163], v[184:187], v[76:79]
	v_mfma_f32_16x16x32_bf16 v[68:71], v[156:159], v[188:191], v[68:71]
	v_mfma_f32_16x16x32_bf16 v[68:71], v[160:163], v[192:195], v[68:71]
	s_barrier
	s_add_i32 s66, s66, s15
	s_mov_b32 m0, s66
	ds_read_b128 v[164:167], v230 offset:16384
	ds_read_b128 v[168:171], v230 offset:17408
	ds_read_b128 v[172:175], v230 offset:18432
	ds_read_b128 v[176:179], v230 offset:19456
	ds_read_b128 v[180:183], v230 offset:20480
	ds_read_b128 v[184:187], v230 offset:21504
	ds_read_b128 v[188:191], v230 offset:22528
	ds_read_b128 v[192:195], v230 offset:23552
	global_load_lds_dwordx4 v204, s[34:35]
	s_add_i32 m0, s66, 0x2000
	s_add_u32 s66, s34, 0x80000
	s_addc_u32 s67, s35, 0
	s_add_i32 s73, s73, s15
	global_load_lds_dwordx4 v200, s[34:35]
	s_mov_b32 m0, s73
	s_nop 0
	global_load_lds_dwordx4 v204, s[66:67]
	s_add_i32 m0, s73, 0x2000
	s_nop 0
	global_load_lds_dwordx4 v200, s[66:67]
	s_waitcnt vmcnt(6)
	s_waitcnt lgkmcnt(0)
	s_barrier
	v_mfma_f32_16x16x32_bf16 v[64:67], v[132:135], v[164:167], v[64:67]
	v_mfma_f32_16x16x32_bf16 v[64:67], v[136:139], v[168:171], v[64:67]
	v_mfma_f32_16x16x32_bf16 v[56:59], v[132:135], v[172:175], v[56:59]
	v_mfma_f32_16x16x32_bf16 v[56:59], v[136:139], v[176:179], v[56:59]
	v_mfma_f32_16x16x32_bf16 v[48:51], v[132:135], v[180:183], v[48:51]
	v_mfma_f32_16x16x32_bf16 v[48:51], v[136:139], v[184:187], v[48:51]
	v_mfma_f32_16x16x32_bf16 v[40:43], v[132:135], v[188:191], v[40:43]
	v_mfma_f32_16x16x32_bf16 v[40:43], v[136:139], v[192:195], v[40:43]
	v_mfma_f32_16x16x32_bf16 v[60:63], v[140:143], v[164:167], v[60:63]
	v_mfma_f32_16x16x32_bf16 v[60:63], v[144:147], v[168:171], v[60:63]
	v_mfma_f32_16x16x32_bf16 v[52:55], v[140:143], v[172:175], v[52:55]
	v_mfma_f32_16x16x32_bf16 v[52:55], v[144:147], v[176:179], v[52:55]
	v_mfma_f32_16x16x32_bf16 v[44:47], v[140:143], v[180:183], v[44:47]
	v_mfma_f32_16x16x32_bf16 v[44:47], v[144:147], v[184:187], v[44:47]
	v_mfma_f32_16x16x32_bf16 v[36:39], v[140:143], v[188:191], v[36:39]
	v_mfma_f32_16x16x32_bf16 v[36:39], v[144:147], v[192:195], v[36:39]
	v_mfma_f32_16x16x32_bf16 v[32:35], v[148:151], v[164:167], v[32:35]
	v_mfma_f32_16x16x32_bf16 v[32:35], v[152:155], v[168:171], v[32:35]
	v_mfma_f32_16x16x32_bf16 v[28:31], v[156:159], v[164:167], v[28:31]
	v_mfma_f32_16x16x32_bf16 v[28:31], v[160:163], v[168:171], v[28:31]
	v_mfma_f32_16x16x32_bf16 v[24:27], v[148:151], v[172:175], v[24:27]
	v_mfma_f32_16x16x32_bf16 v[24:27], v[152:155], v[176:179], v[24:27]
	v_mfma_f32_16x16x32_bf16 v[20:23], v[156:159], v[172:175], v[20:23]
	v_mfma_f32_16x16x32_bf16 v[20:23], v[160:163], v[176:179], v[20:23]
	v_mfma_f32_16x16x32_bf16 v[16:19], v[148:151], v[180:183], v[16:19]
	v_mfma_f32_16x16x32_bf16 v[16:19], v[152:155], v[184:187], v[16:19]
	v_mfma_f32_16x16x32_bf16 v[12:15], v[156:159], v[180:183], v[12:15]
	v_mfma_f32_16x16x32_bf16 v[12:15], v[160:163], v[184:187], v[12:15]
	v_mfma_f32_16x16x32_bf16 v[8:11], v[148:151], v[188:191], v[8:11]
	v_mfma_f32_16x16x32_bf16 v[8:11], v[152:155], v[192:195], v[8:11]
	v_mfma_f32_16x16x32_bf16 v[2:5], v[156:159], v[188:191], v[4:7]
	v_mfma_f32_16x16x32_bf16 v[2:5], v[160:163], v[192:195], v[2:5]
	s_barrier
	s_add_i32 s66, 0, 0x18000
	v_add_u32_e32 v0, s66, v228
	s_add_i32 s67, 0, 0x1c000
	ds_read_b128 v[132:135], v0
	ds_read_b128 v[136:139], v0 offset:1024
	ds_read_b128 v[140:143], v0 offset:2048
	ds_read_b128 v[144:147], v0 offset:3072
	v_add_u32_e32 v0, s67, v228
	ds_read_b128 v[148:151], v0
	ds_read_b128 v[152:155], v0 offset:1024
	ds_read_b128 v[156:159], v0 offset:2048
	ds_read_b128 v[160:163], v0 offset:3072
	s_mov_b32 m0, s46
	ds_read_b128 v[164:167], v230 offset:32768
	ds_read_b128 v[168:171], v230 offset:33792
	ds_read_b128 v[172:175], v230 offset:34816
	ds_read_b128 v[176:179], v230 offset:35840
	ds_read_b128 v[180:183], v230 offset:36864
	ds_read_b128 v[184:187], v230 offset:37888
	ds_read_b128 v[188:191], v230 offset:38912
	ds_read_b128 v[192:195], v230 offset:39936
	global_load_lds_dwordx4 v206, s[42:43]
	s_mov_b32 m0, s47
	s_nop 0
	global_load_lds_dwordx4 v202, s[42:43]
	s_add_u32 s42, s42, 0x80000
	s_addc_u32 s43, s43, 0
	s_mov_b32 m0, s48
	s_nop 0
	global_load_lds_dwordx4 v206, s[42:43]
	s_mov_b32 m0, s49
	s_nop 0
	global_load_lds_dwordx4 v202, s[42:43]
	s_waitcnt vmcnt(8)
	s_waitcnt lgkmcnt(0)
	s_barrier
	v_mfma_f32_16x16x32_bf16 v[128:131], v[132:135], v[164:167], v[128:131]
	v_mfma_f32_16x16x32_bf16 v[128:131], v[136:139], v[168:171], v[128:131]
	v_mfma_f32_16x16x32_bf16 v[120:123], v[132:135], v[172:175], v[120:123]
	v_mfma_f32_16x16x32_bf16 v[120:123], v[136:139], v[176:179], v[120:123]
	v_mfma_f32_16x16x32_bf16 v[112:115], v[132:135], v[180:183], v[112:115]
	v_mfma_f32_16x16x32_bf16 v[112:115], v[136:139], v[184:187], v[112:115]
	v_mfma_f32_16x16x32_bf16 v[104:107], v[132:135], v[188:191], v[104:107]
	v_mfma_f32_16x16x32_bf16 v[104:107], v[136:139], v[192:195], v[104:107]
	v_mfma_f32_16x16x32_bf16 v[124:127], v[140:143], v[164:167], v[124:127]
	v_mfma_f32_16x16x32_bf16 v[124:127], v[144:147], v[168:171], v[124:127]
	v_mfma_f32_16x16x32_bf16 v[116:119], v[140:143], v[172:175], v[116:119]
	v_mfma_f32_16x16x32_bf16 v[116:119], v[144:147], v[176:179], v[116:119]
	v_mfma_f32_16x16x32_bf16 v[108:111], v[140:143], v[180:183], v[108:111]
	v_mfma_f32_16x16x32_bf16 v[108:111], v[144:147], v[184:187], v[108:111]
	v_mfma_f32_16x16x32_bf16 v[100:103], v[140:143], v[188:191], v[100:103]
	v_mfma_f32_16x16x32_bf16 v[100:103], v[144:147], v[192:195], v[100:103]
	v_mfma_f32_16x16x32_bf16 v[96:99], v[148:151], v[164:167], v[96:99]
	v_mfma_f32_16x16x32_bf16 v[96:99], v[152:155], v[168:171], v[96:99]
	v_mfma_f32_16x16x32_bf16 v[88:91], v[148:151], v[172:175], v[88:91]
	v_mfma_f32_16x16x32_bf16 v[88:91], v[152:155], v[176:179], v[88:91]
	v_mfma_f32_16x16x32_bf16 v[80:83], v[148:151], v[180:183], v[80:83]
	v_mfma_f32_16x16x32_bf16 v[80:83], v[152:155], v[184:187], v[80:83]
	v_mfma_f32_16x16x32_bf16 v[72:75], v[148:151], v[188:191], v[72:75]
	v_mfma_f32_16x16x32_bf16 v[72:75], v[152:155], v[192:195], v[72:75]
	v_mfma_f32_16x16x32_bf16 v[92:95], v[156:159], v[164:167], v[92:95]
	v_mfma_f32_16x16x32_bf16 v[92:95], v[160:163], v[168:171], v[92:95]
	v_mfma_f32_16x16x32_bf16 v[84:87], v[156:159], v[172:175], v[84:87]
	v_mfma_f32_16x16x32_bf16 v[84:87], v[160:163], v[176:179], v[84:87]
	v_mfma_f32_16x16x32_bf16 v[76:79], v[156:159], v[180:183], v[76:79]
	v_mfma_f32_16x16x32_bf16 v[76:79], v[160:163], v[184:187], v[76:79]
	v_mfma_f32_16x16x32_bf16 v[68:71], v[156:159], v[188:191], v[68:71]
	v_mfma_f32_16x16x32_bf16 v[68:71], v[160:163], v[192:195], v[68:71]
	s_barrier
	s_add_i32 s42, s66, s15
	s_add_u32 s98, s34, 0x80
	s_addc_u32 s99, s35, 0
	s_mov_b32 m0, s42
	ds_read_b128 v[164:167], v230 offset:49152
	ds_read_b128 v[168:171], v230 offset:50176
	ds_read_b128 v[172:175], v230 offset:51200
	ds_read_b128 v[176:179], v230 offset:52224
	ds_read_b128 v[180:183], v230 offset:53248
	ds_read_b128 v[184:187], v230 offset:54272
	ds_read_b128 v[188:191], v230 offset:55296
	ds_read_b128 v[192:195], v230 offset:56320
	global_load_lds_dwordx4 v204, s[98:99]
	s_add_i32 m0, s42, 0x2000
	s_add_u32 s34, s34, 0x80080
	s_addc_u32 s35, s35, 0
	s_add_i32 s42, s67, s15
	global_load_lds_dwordx4 v200, s[98:99]
	s_mov_b32 m0, s42
	s_nop 0
	global_load_lds_dwordx4 v204, s[34:35]
	s_add_i32 m0, s42, 0x2000
	s_nop 0
	global_load_lds_dwordx4 v200, s[34:35]
	s_waitcnt vmcnt(6)
	s_waitcnt lgkmcnt(0)
	s_barrier
	v_mfma_f32_16x16x32_bf16 v[64:67], v[132:135], v[164:167], v[64:67]
	v_mfma_f32_16x16x32_bf16 v[64:67], v[136:139], v[168:171], v[64:67]
	v_mfma_f32_16x16x32_bf16 v[56:59], v[132:135], v[172:175], v[56:59]
	v_mfma_f32_16x16x32_bf16 v[56:59], v[136:139], v[176:179], v[56:59]
	v_mfma_f32_16x16x32_bf16 v[48:51], v[132:135], v[180:183], v[48:51]
	v_mfma_f32_16x16x32_bf16 v[48:51], v[136:139], v[184:187], v[48:51]
	v_mfma_f32_16x16x32_bf16 v[40:43], v[132:135], v[188:191], v[40:43]
	v_mfma_f32_16x16x32_bf16 v[40:43], v[136:139], v[192:195], v[40:43]
	v_mfma_f32_16x16x32_bf16 v[60:63], v[140:143], v[164:167], v[60:63]
	v_mfma_f32_16x16x32_bf16 v[60:63], v[144:147], v[168:171], v[60:63]
	v_mfma_f32_16x16x32_bf16 v[52:55], v[140:143], v[172:175], v[52:55]
	v_mfma_f32_16x16x32_bf16 v[52:55], v[144:147], v[176:179], v[52:55]
	v_mfma_f32_16x16x32_bf16 v[44:47], v[140:143], v[180:183], v[44:47]
	v_mfma_f32_16x16x32_bf16 v[44:47], v[144:147], v[184:187], v[44:47]
	v_mfma_f32_16x16x32_bf16 v[36:39], v[140:143], v[188:191], v[36:39]
	v_mfma_f32_16x16x32_bf16 v[36:39], v[144:147], v[192:195], v[36:39]
	v_mfma_f32_16x16x32_bf16 v[32:35], v[148:151], v[164:167], v[32:35]
	v_mfma_f32_16x16x32_bf16 v[32:35], v[152:155], v[168:171], v[32:35]
	v_mfma_f32_16x16x32_bf16 v[28:31], v[156:159], v[164:167], v[28:31]
	v_mfma_f32_16x16x32_bf16 v[28:31], v[160:163], v[168:171], v[28:31]
	v_mfma_f32_16x16x32_bf16 v[24:27], v[148:151], v[172:175], v[24:27]
	v_mfma_f32_16x16x32_bf16 v[24:27], v[152:155], v[176:179], v[24:27]
	v_mfma_f32_16x16x32_bf16 v[20:23], v[156:159], v[172:175], v[20:23]
	v_mfma_f32_16x16x32_bf16 v[20:23], v[160:163], v[176:179], v[20:23]
	v_mfma_f32_16x16x32_bf16 v[16:19], v[148:151], v[180:183], v[16:19]
	v_mfma_f32_16x16x32_bf16 v[16:19], v[152:155], v[184:187], v[16:19]
	v_mfma_f32_16x16x32_bf16 v[12:15], v[156:159], v[180:183], v[12:15]
	v_mfma_f32_16x16x32_bf16 v[12:15], v[160:163], v[184:187], v[12:15]
	v_mfma_f32_16x16x32_bf16 v[6:9], v[148:151], v[188:191], v[8:11]
	v_mfma_f32_16x16x32_bf16 v[8:11], v[152:155], v[192:195], v[6:9]
	v_mfma_f32_16x16x32_bf16 v[2:5], v[156:159], v[188:191], v[2:5]
	v_mfma_f32_16x16x32_bf16 v[4:7], v[160:163], v[192:195], v[2:5]
	s_barrier
	s_add_i32 s57, s57, 2
	s_add_u32 s30, s30, 0x100
	s_addc_u32 s31, s31, 0
	s_add_u32 s55, s55, 0x100
	s_addc_u32 s56, s56, 0
	s_cmp_gt_u32 s57, 29
	s_cbranch_scc0 .LBB0_577
	s_and_b64 vcc, exec, s[20:21]
	s_cbranch_vccz .LBB0_580
	s_barrier

.LBB0_779:
	s_add_u32 s98, s30, 0xfff80000
	s_addc_u32 s99, s31, -1
	s_add_u32 s34, s30, 0xfff80080
	s_addc_u32 s35, s31, -1
	s_add_i32 s66, 0, 0x10000
	s_cmp_eq_u32 s57, 28
	s_cselect_b32 s43, s25, s35
	s_cselect_b32 s42, s53, s34
	s_cselect_b32 s35, s23, s56
	s_cselect_b32 s34, s54, s55
	s_add_i32 s73, 0, 0x14000
	v_add_u32_e32 v114, s66, v157
	v_add_u32_e32 v156, s73, v157
	ds_read_b128 v[90:93], v114
	ds_read_b128 v[94:97], v114 offset:1024
	ds_read_b128 v[106:109], v114 offset:2048
	ds_read_b128 v[114:117], v114 offset:3072
	ds_read_b128 v[162:165], v156
	ds_read_b128 v[166:169], v156 offset:1024
	ds_read_b128 v[170:173], v156 offset:2048
	ds_read_b128 v[174:177], v156 offset:3072
	s_mov_b32 m0, s50
	ds_read_b128 v[178:181], v161
	ds_read_b128 v[182:185], v161 offset:1024
	ds_read_b128 v[186:189], v161 offset:2048
	ds_read_b128 v[190:193], v161 offset:3072
	ds_read_b128 v[200:203], v161 offset:4096
	ds_read_b128 v[204:207], v161 offset:5120
	ds_read_b128 v[208:211], v161 offset:6144
	ds_read_b128 v[212:215], v161 offset:7168
	global_load_lds_dwordx4 v150, s[98:99]
	s_mov_b32 m0, s51
	s_nop 0
	global_load_lds_dwordx4 v148, s[98:99]
	s_add_i32 m0, s14, 0xc000
	s_nop 0
	global_load_lds_dwordx4 v152, s[30:31]
	s_add_i32 m0, s14, 0xe000
	s_nop 0
	global_load_lds_dwordx4 v154, s[30:31]
	s_waitcnt vmcnt(8)
	s_waitcnt lgkmcnt(0)
	s_barrier
	v_mfma_i32_16x16x64_i8 v[142:145], v[90:93], v[178:181], v[142:145]
	v_mfma_i32_16x16x64_i8 v[142:145], v[94:97], v[182:185], v[142:145]
	v_mfma_i32_16x16x64_i8 v[126:129], v[90:93], v[186:189], v[126:129]
	v_mfma_i32_16x16x64_i8 v[126:129], v[94:97], v[190:193], v[126:129]
	v_mfma_i32_16x16x64_i8 v[102:105], v[90:93], v[200:203], v[102:105]
	v_mfma_i32_16x16x64_i8 v[102:105], v[94:97], v[204:207], v[102:105]
	v_mfma_i32_16x16x64_i8 v[78:81], v[90:93], v[208:211], v[78:81]
	v_mfma_i32_16x16x64_i8 v[78:81], v[94:97], v[212:215], v[78:81]
	v_mfma_i32_16x16x64_i8 v[138:141], v[106:109], v[178:181], v[138:141]
	v_mfma_i32_16x16x64_i8 v[138:141], v[114:117], v[182:185], v[138:141]
	v_mfma_i32_16x16x64_i8 v[122:125], v[106:109], v[186:189], v[122:125]
	v_mfma_i32_16x16x64_i8 v[122:125], v[114:117], v[190:193], v[122:125]
	v_mfma_i32_16x16x64_i8 v[98:101], v[106:109], v[200:203], v[98:101]
	v_mfma_i32_16x16x64_i8 v[98:101], v[114:117], v[204:207], v[98:101]
	v_mfma_i32_16x16x64_i8 v[74:77], v[106:109], v[208:211], v[74:77]
	v_mfma_i32_16x16x64_i8 v[74:77], v[114:117], v[212:215], v[74:77]
	v_mfma_i32_16x16x64_i8 v[134:137], v[162:165], v[178:181], v[134:137]
	v_mfma_i32_16x16x64_i8 v[134:137], v[166:169], v[182:185], v[134:137]
	v_mfma_i32_16x16x64_i8 v[118:121], v[162:165], v[186:189], v[118:121]
	v_mfma_i32_16x16x64_i8 v[118:121], v[166:169], v[190:193], v[118:121]
	v_mfma_i32_16x16x64_i8 v[86:89], v[162:165], v[200:203], v[86:89]
	v_mfma_i32_16x16x64_i8 v[86:89], v[166:169], v[204:207], v[86:89]
	v_mfma_i32_16x16x64_i8 v[70:73], v[162:165], v[208:211], v[70:73]
	v_mfma_i32_16x16x64_i8 v[70:73], v[166:169], v[212:215], v[70:73]
	v_mfma_i32_16x16x64_i8 v[130:133], v[170:173], v[178:181], v[130:133]
	v_mfma_i32_16x16x64_i8 v[130:133], v[174:177], v[182:185], v[130:133]
	v_mfma_i32_16x16x64_i8 v[110:113], v[170:173], v[186:189], v[110:113]
	v_mfma_i32_16x16x64_i8 v[110:113], v[174:177], v[190:193], v[110:113]
	v_mfma_i32_16x16x64_i8 v[82:85], v[170:173], v[200:203], v[82:85]
	v_mfma_i32_16x16x64_i8 v[82:85], v[174:177], v[204:207], v[82:85]
	v_mfma_i32_16x16x64_i8 v[66:69], v[170:173], v[208:211], v[66:69]
	v_mfma_i32_16x16x64_i8 v[66:69], v[174:177], v[212:215], v[66:69]
	s_barrier
	s_add_i32 s66, s66, s9
	s_mov_b32 m0, s66
	ds_read_b128 v[178:181], v161 offset:16384
	ds_read_b128 v[182:185], v161 offset:17408
	ds_read_b128 v[186:189], v161 offset:18432
	ds_read_b128 v[190:193], v161 offset:19456
	ds_read_b128 v[200:203], v161 offset:20480
	ds_read_b128 v[204:207], v161 offset:21504
	ds_read_b128 v[208:211], v161 offset:22528
	ds_read_b128 v[212:215], v161 offset:23552
	global_load_lds_dwordx4 v0, s[34:35]
	s_add_i32 m0, s66, 0x2000
	s_add_u32 s66, s34, 0x80000
	s_addc_u32 s67, s35, 0
	s_add_i32 s73, s73, s9
	global_load_lds_dwordx4 v146, s[34:35]
	s_mov_b32 m0, s73
	s_nop 0
	global_load_lds_dwordx4 v0, s[66:67]
	s_add_i32 m0, s73, 0x2000
	s_nop 0
	global_load_lds_dwordx4 v146, s[66:67]
	s_waitcnt vmcnt(6)
	s_waitcnt lgkmcnt(0)
	s_barrier
	v_mfma_i32_16x16x64_i8 v[62:65], v[90:93], v[178:181], v[62:65]
	v_mfma_i32_16x16x64_i8 v[62:65], v[94:97], v[182:185], v[62:65]
	v_mfma_i32_16x16x64_i8 v[46:49], v[90:93], v[186:189], v[46:49]
	v_mfma_i32_16x16x64_i8 v[46:49], v[94:97], v[190:193], v[46:49]
	v_mfma_i32_16x16x64_i8 v[30:33], v[90:93], v[200:203], v[30:33]
	v_mfma_i32_16x16x64_i8 v[30:33], v[94:97], v[204:207], v[30:33]
	v_mfma_i32_16x16x64_i8 v[14:17], v[90:93], v[208:211], v[14:17]
	v_mfma_i32_16x16x64_i8 v[14:17], v[94:97], v[212:215], v[14:17]
	v_mfma_i32_16x16x64_i8 v[58:61], v[106:109], v[178:181], v[58:61]
	v_mfma_i32_16x16x64_i8 v[58:61], v[114:117], v[182:185], v[58:61]
	v_mfma_i32_16x16x64_i8 v[42:45], v[106:109], v[186:189], v[42:45]
	v_mfma_i32_16x16x64_i8 v[42:45], v[114:117], v[190:193], v[42:45]
	v_mfma_i32_16x16x64_i8 v[26:29], v[106:109], v[200:203], v[26:29]
	v_mfma_i32_16x16x64_i8 v[26:29], v[114:117], v[204:207], v[26:29]
	v_mfma_i32_16x16x64_i8 v[10:13], v[106:109], v[208:211], v[10:13]
	v_mfma_i32_16x16x64_i8 v[10:13], v[114:117], v[212:215], v[10:13]
	v_mfma_i32_16x16x64_i8 v[54:57], v[162:165], v[178:181], v[54:57]
	v_mfma_i32_16x16x64_i8 v[54:57], v[166:169], v[182:185], v[54:57]
	v_mfma_i32_16x16x64_i8 v[38:41], v[162:165], v[186:189], v[38:41]
	v_mfma_i32_16x16x64_i8 v[38:41], v[166:169], v[190:193], v[38:41]
	v_mfma_i32_16x16x64_i8 v[22:25], v[162:165], v[200:203], v[22:25]
	v_mfma_i32_16x16x64_i8 v[22:25], v[166:169], v[204:207], v[22:25]
	v_mfma_i32_16x16x64_i8 v[6:9], v[162:165], v[208:211], v[6:9]
	v_mfma_i32_16x16x64_i8 v[6:9], v[166:169], v[212:215], v[6:9]
	v_mfma_i32_16x16x64_i8 v[50:53], v[170:173], v[178:181], v[50:53]
	v_mfma_i32_16x16x64_i8 v[50:53], v[174:177], v[182:185], v[50:53]
	v_mfma_i32_16x16x64_i8 v[34:37], v[170:173], v[186:189], v[34:37]
	v_mfma_i32_16x16x64_i8 v[34:37], v[174:177], v[190:193], v[34:37]
	v_mfma_i32_16x16x64_i8 v[18:21], v[170:173], v[200:203], v[18:21]
	v_mfma_i32_16x16x64_i8 v[18:21], v[174:177], v[204:207], v[18:21]
	v_mfma_i32_16x16x64_i8 v[2:5], v[170:173], v[208:211], v[2:5]
	v_mfma_i32_16x16x64_i8 v[2:5], v[174:177], v[212:215], v[2:5]
	s_barrier
	s_add_i32 s66, 0, 0x18000
	s_add_i32 s67, 0, 0x1c000
	v_add_u32_e32 v114, s66, v157
	v_add_u32_e32 v156, s67, v157
	ds_read_b128 v[90:93], v114
	ds_read_b128 v[94:97], v114 offset:1024
	ds_read_b128 v[106:109], v114 offset:2048
	ds_read_b128 v[114:117], v114 offset:3072
	ds_read_b128 v[162:165], v156
	ds_read_b128 v[166:169], v156 offset:1024
	ds_read_b128 v[170:173], v156 offset:2048
	ds_read_b128 v[174:177], v156 offset:3072
	s_mov_b32 m0, s14
	ds_read_b128 v[178:181], v161 offset:32768
	ds_read_b128 v[182:185], v161 offset:33792
	ds_read_b128 v[186:189], v161 offset:34816
	ds_read_b128 v[190:193], v161 offset:35840
	ds_read_b128 v[200:203], v161 offset:36864
	ds_read_b128 v[204:207], v161 offset:37888
	ds_read_b128 v[208:211], v161 offset:38912
	ds_read_b128 v[212:215], v161 offset:39936
	global_load_lds_dwordx4 v150, s[42:43]
	s_mov_b32 m0, s15
	s_nop 0
	global_load_lds_dwordx4 v148, s[42:43]
	s_add_u32 s42, s42, 0x80000
	s_addc_u32 s43, s43, 0
	s_mov_b32 m0, s46
	s_nop 0
	global_load_lds_dwordx4 v150, s[42:43]
	s_mov_b32 m0, s47
	s_nop 0
	global_load_lds_dwordx4 v148, s[42:43]
	s_waitcnt vmcnt(8)
	s_waitcnt lgkmcnt(0)
	s_barrier
	v_mfma_i32_16x16x64_i8 v[142:145], v[90:93], v[178:181], v[142:145]
	v_mfma_i32_16x16x64_i8 v[142:145], v[94:97], v[182:185], v[142:145]
	v_mfma_i32_16x16x64_i8 v[126:129], v[90:93], v[186:189], v[126:129]
	v_mfma_i32_16x16x64_i8 v[126:129], v[94:97], v[190:193], v[126:129]
	v_mfma_i32_16x16x64_i8 v[102:105], v[90:93], v[200:203], v[102:105]
	v_mfma_i32_16x16x64_i8 v[102:105], v[94:97], v[204:207], v[102:105]
	v_mfma_i32_16x16x64_i8 v[78:81], v[90:93], v[208:211], v[78:81]
	v_mfma_i32_16x16x64_i8 v[78:81], v[94:97], v[212:215], v[78:81]
	v_mfma_i32_16x16x64_i8 v[138:141], v[106:109], v[178:181], v[138:141]
	v_mfma_i32_16x16x64_i8 v[138:141], v[114:117], v[182:185], v[138:141]
	v_mfma_i32_16x16x64_i8 v[122:125], v[106:109], v[186:189], v[122:125]
	v_mfma_i32_16x16x64_i8 v[122:125], v[114:117], v[190:193], v[122:125]
	v_mfma_i32_16x16x64_i8 v[98:101], v[106:109], v[200:203], v[98:101]
	v_mfma_i32_16x16x64_i8 v[98:101], v[114:117], v[204:207], v[98:101]
	v_mfma_i32_16x16x64_i8 v[74:77], v[106:109], v[208:211], v[74:77]
	v_mfma_i32_16x16x64_i8 v[74:77], v[114:117], v[212:215], v[74:77]
	v_mfma_i32_16x16x64_i8 v[134:137], v[162:165], v[178:181], v[134:137]
	v_mfma_i32_16x16x64_i8 v[134:137], v[166:169], v[182:185], v[134:137]
	v_mfma_i32_16x16x64_i8 v[118:121], v[162:165], v[186:189], v[118:121]
	v_mfma_i32_16x16x64_i8 v[118:121], v[166:169], v[190:193], v[118:121]
	v_mfma_i32_16x16x64_i8 v[86:89], v[162:165], v[200:203], v[86:89]
	v_mfma_i32_16x16x64_i8 v[86:89], v[166:169], v[204:207], v[86:89]
	v_mfma_i32_16x16x64_i8 v[70:73], v[162:165], v[208:211], v[70:73]
	v_mfma_i32_16x16x64_i8 v[70:73], v[166:169], v[212:215], v[70:73]
	v_mfma_i32_16x16x64_i8 v[130:133], v[170:173], v[178:181], v[130:133]
	v_mfma_i32_16x16x64_i8 v[130:133], v[174:177], v[182:185], v[130:133]
	v_mfma_i32_16x16x64_i8 v[110:113], v[170:173], v[186:189], v[110:113]
	v_mfma_i32_16x16x64_i8 v[110:113], v[174:177], v[190:193], v[110:113]
	v_mfma_i32_16x16x64_i8 v[82:85], v[170:173], v[200:203], v[82:85]
	v_mfma_i32_16x16x64_i8 v[82:85], v[174:177], v[204:207], v[82:85]
	v_mfma_i32_16x16x64_i8 v[66:69], v[170:173], v[208:211], v[66:69]
	v_mfma_i32_16x16x64_i8 v[66:69], v[174:177], v[212:215], v[66:69]
	s_barrier
	s_add_u32 s98, s34, 0x80
	s_addc_u32 s99, s35, 0
	s_add_i32 s42, s66, s9
	s_mov_b32 m0, s42
	ds_read_b128 v[178:181], v161 offset:49152
	ds_read_b128 v[182:185], v161 offset:50176
	ds_read_b128 v[186:189], v161 offset:51200
	ds_read_b128 v[190:193], v161 offset:52224
	ds_read_b128 v[200:203], v161 offset:53248
	ds_read_b128 v[204:207], v161 offset:54272
	ds_read_b128 v[208:211], v161 offset:55296
	ds_read_b128 v[212:215], v161 offset:56320
	global_load_lds_dwordx4 v0, s[98:99]
	s_add_i32 m0, s42, 0x2000
	s_add_u32 s34, s34, 0x80080
	s_addc_u32 s35, s35, 0
	s_add_i32 s42, s67, s9
	global_load_lds_dwordx4 v146, s[98:99]
	s_mov_b32 m0, s42
	s_nop 0
	global_load_lds_dwordx4 v0, s[34:35]
	s_add_i32 m0, s42, 0x2000
	s_nop 0
	global_load_lds_dwordx4 v146, s[34:35]
	s_waitcnt vmcnt(6)
	s_waitcnt lgkmcnt(0)
	s_barrier
	v_mfma_i32_16x16x64_i8 v[62:65], v[90:93], v[178:181], v[62:65]
	v_mfma_i32_16x16x64_i8 v[62:65], v[94:97], v[182:185], v[62:65]
	v_mfma_i32_16x16x64_i8 v[46:49], v[90:93], v[186:189], v[46:49]
	v_mfma_i32_16x16x64_i8 v[46:49], v[94:97], v[190:193], v[46:49]
	v_mfma_i32_16x16x64_i8 v[30:33], v[90:93], v[200:203], v[30:33]
	v_mfma_i32_16x16x64_i8 v[30:33], v[94:97], v[204:207], v[30:33]
	v_mfma_i32_16x16x64_i8 v[14:17], v[90:93], v[208:211], v[14:17]
	v_mfma_i32_16x16x64_i8 v[14:17], v[94:97], v[212:215], v[14:17]
	v_mfma_i32_16x16x64_i8 v[58:61], v[106:109], v[178:181], v[58:61]
	v_mfma_i32_16x16x64_i8 v[58:61], v[114:117], v[182:185], v[58:61]
	v_mfma_i32_16x16x64_i8 v[42:45], v[106:109], v[186:189], v[42:45]
	v_mfma_i32_16x16x64_i8 v[42:45], v[114:117], v[190:193], v[42:45]
	v_mfma_i32_16x16x64_i8 v[26:29], v[106:109], v[200:203], v[26:29]
	v_mfma_i32_16x16x64_i8 v[26:29], v[114:117], v[204:207], v[26:29]
	v_mfma_i32_16x16x64_i8 v[10:13], v[106:109], v[208:211], v[10:13]
	v_mfma_i32_16x16x64_i8 v[10:13], v[114:117], v[212:215], v[10:13]
	v_mfma_i32_16x16x64_i8 v[54:57], v[162:165], v[178:181], v[54:57]
	v_mfma_i32_16x16x64_i8 v[54:57], v[166:169], v[182:185], v[54:57]
	v_mfma_i32_16x16x64_i8 v[38:41], v[162:165], v[186:189], v[38:41]
	v_mfma_i32_16x16x64_i8 v[38:41], v[166:169], v[190:193], v[38:41]
	v_mfma_i32_16x16x64_i8 v[22:25], v[162:165], v[200:203], v[22:25]
	v_mfma_i32_16x16x64_i8 v[22:25], v[166:169], v[204:207], v[22:25]
	v_mfma_i32_16x16x64_i8 v[6:9], v[162:165], v[208:211], v[6:9]
	v_mfma_i32_16x16x64_i8 v[6:9], v[166:169], v[212:215], v[6:9]
	v_mfma_i32_16x16x64_i8 v[50:53], v[170:173], v[178:181], v[50:53]
	v_mfma_i32_16x16x64_i8 v[50:53], v[174:177], v[182:185], v[50:53]
	v_mfma_i32_16x16x64_i8 v[34:37], v[170:173], v[186:189], v[34:37]
	v_mfma_i32_16x16x64_i8 v[34:37], v[174:177], v[190:193], v[34:37]
	v_mfma_i32_16x16x64_i8 v[18:21], v[170:173], v[200:203], v[18:21]
	v_mfma_i32_16x16x64_i8 v[18:21], v[174:177], v[204:207], v[18:21]
	v_mfma_i32_16x16x64_i8 v[2:5], v[170:173], v[208:211], v[2:5]
	v_mfma_i32_16x16x64_i8 v[2:5], v[174:177], v[212:215], v[2:5]
	s_barrier
	s_add_i32 s57, s57, 2
	s_add_u32 s30, s30, 0x100
	s_addc_u32 s31, s31, 0
	s_add_u32 s55, s55, 0x100
	s_addc_u32 s56, s56, 0
	s_cmp_gt_u32 s57, 29
	s_cbranch_scc0 .LBB0_779
	s_and_b64 vcc, exec, s[20:21]
	s_mov_b32 s54, 0x5c401000
	s_cbranch_vccz .LBB0_782
	s_barrier

.LBB0_801:
	s_add_u32 s98, s30, 0xfff00000
	s_addc_u32 s99, s31, -1
	s_add_u32 s34, s30, 0xfff00080
	s_addc_u32 s35, s31, -1
	s_add_i32 s54, 0, 0x10000
	s_cmp_eq_u32 s53, 60
	s_cselect_b32 s41, s25, s35
	s_cselect_b32 s40, s49, s34
	s_cselect_b32 s35, s23, s52
	s_cselect_b32 s34, s50, s51
	s_add_i32 s56, 0, 0x14000
	v_add_u32_e32 v156, s54, v141
	v_add_u32_e32 v172, s56, v141
	ds_read_b128 v[144:147], v156
	ds_read_b128 v[148:151], v156 offset:1024
	ds_read_b128 v[152:155], v156 offset:2048
	ds_read_b128 v[156:159], v156 offset:3072
	ds_read_b128 v[160:163], v172
	ds_read_b128 v[164:167], v172 offset:1024
	ds_read_b128 v[168:171], v172 offset:2048
	ds_read_b128 v[172:175], v172 offset:3072
	s_mov_b32 m0, s42
	ds_read_b128 v[176:179], v143
	ds_read_b128 v[180:183], v143 offset:1024
	ds_read_b128 v[184:187], v143 offset:2048
	ds_read_b128 v[188:191], v143 offset:3072
	ds_read_b128 v[192:195], v143 offset:4096
	ds_read_b128 v[200:203], v143 offset:5120
	ds_read_b128 v[204:207], v143 offset:6144
	ds_read_b128 v[208:211], v143 offset:7168
	global_load_lds_dwordx4 v134, s[98:99]
	s_mov_b32 m0, s43
	s_nop 0
	global_load_lds_dwordx4 v132, s[98:99]
	s_add_i32 m0, s14, 0xc000
	s_nop 0
	global_load_lds_dwordx4 v136, s[30:31]
	s_add_i32 m0, s14, 0xe000
	s_nop 0
	global_load_lds_dwordx4 v138, s[30:31]
	s_waitcnt vmcnt(8)
	s_waitcnt lgkmcnt(0)
	s_barrier
	v_mfma_f32_16x16x32_bf16 v[126:129], v[144:147], v[176:179], v[126:129]
	v_mfma_f32_16x16x32_bf16 v[126:129], v[148:151], v[180:183], v[126:129]
	v_mfma_f32_16x16x32_bf16 v[118:121], v[144:147], v[184:187], v[118:121]
	v_mfma_f32_16x16x32_bf16 v[118:121], v[148:151], v[188:191], v[118:121]
	v_mfma_f32_16x16x32_bf16 v[102:105], v[144:147], v[192:195], v[102:105]
	v_mfma_f32_16x16x32_bf16 v[102:105], v[148:151], v[200:203], v[102:105]
	v_mfma_f32_16x16x32_bf16 v[86:89], v[144:147], v[204:207], v[86:89]
	v_mfma_f32_16x16x32_bf16 v[86:89], v[148:151], v[208:211], v[86:89]
	v_mfma_f32_16x16x32_bf16 v[122:125], v[152:155], v[176:179], v[122:125]
	v_mfma_f32_16x16x32_bf16 v[122:125], v[156:159], v[180:183], v[122:125]
	v_mfma_f32_16x16x32_bf16 v[114:117], v[152:155], v[184:187], v[114:117]
	v_mfma_f32_16x16x32_bf16 v[114:117], v[156:159], v[188:191], v[114:117]
	v_mfma_f32_16x16x32_bf16 v[98:101], v[152:155], v[192:195], v[98:101]
	v_mfma_f32_16x16x32_bf16 v[98:101], v[156:159], v[200:203], v[98:101]
	v_mfma_f32_16x16x32_bf16 v[82:85], v[152:155], v[204:207], v[82:85]
	v_mfma_f32_16x16x32_bf16 v[82:85], v[156:159], v[208:211], v[82:85]
	v_mfma_f32_16x16x32_bf16 v[110:113], v[160:163], v[176:179], v[110:113]
	v_mfma_f32_16x16x32_bf16 v[110:113], v[164:167], v[180:183], v[110:113]
	v_mfma_f32_16x16x32_bf16 v[94:97], v[160:163], v[184:187], v[94:97]
	v_mfma_f32_16x16x32_bf16 v[94:97], v[164:167], v[188:191], v[94:97]
	v_mfma_f32_16x16x32_bf16 v[78:81], v[160:163], v[192:195], v[78:81]
	v_mfma_f32_16x16x32_bf16 v[78:81], v[164:167], v[200:203], v[78:81]
	v_mfma_f32_16x16x32_bf16 v[70:73], v[160:163], v[204:207], v[70:73]
	v_mfma_f32_16x16x32_bf16 v[70:73], v[164:167], v[208:211], v[70:73]
	v_mfma_f32_16x16x32_bf16 v[106:109], v[168:171], v[176:179], v[106:109]
	v_mfma_f32_16x16x32_bf16 v[106:109], v[172:175], v[180:183], v[106:109]
	v_mfma_f32_16x16x32_bf16 v[90:93], v[168:171], v[184:187], v[90:93]
	v_mfma_f32_16x16x32_bf16 v[90:93], v[172:175], v[188:191], v[90:93]
	v_mfma_f32_16x16x32_bf16 v[74:77], v[168:171], v[192:195], v[74:77]
	v_mfma_f32_16x16x32_bf16 v[74:77], v[172:175], v[200:203], v[74:77]
	v_mfma_f32_16x16x32_bf16 v[66:69], v[168:171], v[204:207], v[66:69]
	v_mfma_f32_16x16x32_bf16 v[66:69], v[172:175], v[208:211], v[66:69]
	s_barrier
	s_add_i32 s54, s54, s9
	s_mov_b32 m0, s54
	ds_read_b128 v[176:179], v143 offset:16384
	ds_read_b128 v[180:183], v143 offset:17408
	ds_read_b128 v[184:187], v143 offset:18432
	ds_read_b128 v[188:191], v143 offset:19456
	ds_read_b128 v[192:195], v143 offset:20480
	ds_read_b128 v[200:203], v143 offset:21504
	ds_read_b128 v[204:207], v143 offset:22528
	ds_read_b128 v[208:211], v143 offset:23552
	global_load_lds_dwordx4 v0, s[34:35]
	s_add_i32 m0, s54, 0x2000
	s_add_u32 s54, s34, 0x100000
	s_addc_u32 s55, s35, 0
	s_add_i32 s56, s56, s9
	global_load_lds_dwordx4 v130, s[34:35]
	s_mov_b32 m0, s56
	s_nop 0
	global_load_lds_dwordx4 v0, s[54:55]
	s_add_i32 m0, s56, 0x2000
	s_nop 0
	global_load_lds_dwordx4 v130, s[54:55]
	s_waitcnt vmcnt(6)
	s_waitcnt lgkmcnt(0)
	s_barrier
	v_mfma_f32_16x16x32_bf16 v[62:65], v[144:147], v[176:179], v[62:65]
	v_mfma_f32_16x16x32_bf16 v[62:65], v[148:151], v[180:183], v[62:65]
	v_mfma_f32_16x16x32_bf16 v[54:57], v[144:147], v[184:187], v[54:57]
	v_mfma_f32_16x16x32_bf16 v[54:57], v[148:151], v[188:191], v[54:57]
	v_mfma_f32_16x16x32_bf16 v[38:41], v[144:147], v[192:195], v[38:41]
	v_mfma_f32_16x16x32_bf16 v[38:41], v[148:151], v[200:203], v[38:41]
	v_mfma_f32_16x16x32_bf16 v[22:25], v[144:147], v[204:207], v[22:25]
	v_mfma_f32_16x16x32_bf16 v[22:25], v[148:151], v[208:211], v[22:25]
	v_mfma_f32_16x16x32_bf16 v[58:61], v[152:155], v[176:179], v[58:61]
	v_mfma_f32_16x16x32_bf16 v[58:61], v[156:159], v[180:183], v[58:61]
	v_mfma_f32_16x16x32_bf16 v[50:53], v[152:155], v[184:187], v[50:53]
	v_mfma_f32_16x16x32_bf16 v[50:53], v[156:159], v[188:191], v[50:53]
	v_mfma_f32_16x16x32_bf16 v[34:37], v[152:155], v[192:195], v[34:37]
	v_mfma_f32_16x16x32_bf16 v[34:37], v[156:159], v[200:203], v[34:37]
	v_mfma_f32_16x16x32_bf16 v[18:21], v[152:155], v[204:207], v[18:21]
	v_mfma_f32_16x16x32_bf16 v[18:21], v[156:159], v[208:211], v[18:21]
	v_mfma_f32_16x16x32_bf16 v[46:49], v[160:163], v[176:179], v[46:49]
	v_mfma_f32_16x16x32_bf16 v[46:49], v[164:167], v[180:183], v[46:49]
	v_mfma_f32_16x16x32_bf16 v[30:33], v[160:163], v[184:187], v[30:33]
	v_mfma_f32_16x16x32_bf16 v[30:33], v[164:167], v[188:191], v[30:33]
	v_mfma_f32_16x16x32_bf16 v[14:17], v[160:163], v[192:195], v[14:17]
	v_mfma_f32_16x16x32_bf16 v[14:17], v[164:167], v[200:203], v[14:17]
	v_mfma_f32_16x16x32_bf16 v[6:9], v[160:163], v[204:207], v[6:9]
	v_mfma_f32_16x16x32_bf16 v[6:9], v[164:167], v[208:211], v[6:9]
	v_mfma_f32_16x16x32_bf16 v[42:45], v[168:171], v[176:179], v[42:45]
	v_mfma_f32_16x16x32_bf16 v[42:45], v[172:175], v[180:183], v[42:45]
	v_mfma_f32_16x16x32_bf16 v[26:29], v[168:171], v[184:187], v[26:29]
	v_mfma_f32_16x16x32_bf16 v[26:29], v[172:175], v[188:191], v[26:29]
	v_mfma_f32_16x16x32_bf16 v[10:13], v[168:171], v[192:195], v[10:13]
	v_mfma_f32_16x16x32_bf16 v[10:13], v[172:175], v[200:203], v[10:13]
	v_mfma_f32_16x16x32_bf16 v[2:5], v[168:171], v[204:207], v[2:5]
	v_mfma_f32_16x16x32_bf16 v[2:5], v[172:175], v[208:211], v[2:5]
	s_barrier
	s_add_i32 s54, 0, 0x18000
	s_add_i32 s55, 0, 0x1c000
	v_add_u32_e32 v156, s54, v141
	v_add_u32_e32 v172, s55, v141
	ds_read_b128 v[144:147], v156
	ds_read_b128 v[148:151], v156 offset:1024
	ds_read_b128 v[152:155], v156 offset:2048
	ds_read_b128 v[156:159], v156 offset:3072
	ds_read_b128 v[160:163], v172
	ds_read_b128 v[164:167], v172 offset:1024
	ds_read_b128 v[168:171], v172 offset:2048
	ds_read_b128 v[172:175], v172 offset:3072
	s_mov_b32 m0, s14
	ds_read_b128 v[176:179], v143 offset:32768
	ds_read_b128 v[180:183], v143 offset:33792
	ds_read_b128 v[184:187], v143 offset:34816
	ds_read_b128 v[188:191], v143 offset:35840
	ds_read_b128 v[192:195], v143 offset:36864
	ds_read_b128 v[200:203], v143 offset:37888
	ds_read_b128 v[204:207], v143 offset:38912
	ds_read_b128 v[208:211], v143 offset:39936
	global_load_lds_dwordx4 v134, s[40:41]
	s_mov_b32 m0, s15
	s_nop 0
	global_load_lds_dwordx4 v132, s[40:41]
	s_add_u32 s40, s40, 0x100000
	s_addc_u32 s41, s41, 0
	s_mov_b32 m0, s18
	s_nop 0
	global_load_lds_dwordx4 v134, s[40:41]
	s_mov_b32 m0, s19
	s_nop 0
	global_load_lds_dwordx4 v132, s[40:41]
	s_waitcnt vmcnt(8)
	s_waitcnt lgkmcnt(0)
	s_barrier
	v_mfma_f32_16x16x32_bf16 v[126:129], v[144:147], v[176:179], v[126:129]
	v_mfma_f32_16x16x32_bf16 v[126:129], v[148:151], v[180:183], v[126:129]
	v_mfma_f32_16x16x32_bf16 v[118:121], v[144:147], v[184:187], v[118:121]
	v_mfma_f32_16x16x32_bf16 v[118:121], v[148:151], v[188:191], v[118:121]
	v_mfma_f32_16x16x32_bf16 v[102:105], v[144:147], v[192:195], v[102:105]
	v_mfma_f32_16x16x32_bf16 v[102:105], v[148:151], v[200:203], v[102:105]
	v_mfma_f32_16x16x32_bf16 v[86:89], v[144:147], v[204:207], v[86:89]
	v_mfma_f32_16x16x32_bf16 v[86:89], v[148:151], v[208:211], v[86:89]
	v_mfma_f32_16x16x32_bf16 v[122:125], v[152:155], v[176:179], v[122:125]
	v_mfma_f32_16x16x32_bf16 v[122:125], v[156:159], v[180:183], v[122:125]
	v_mfma_f32_16x16x32_bf16 v[114:117], v[152:155], v[184:187], v[114:117]
	v_mfma_f32_16x16x32_bf16 v[114:117], v[156:159], v[188:191], v[114:117]
	v_mfma_f32_16x16x32_bf16 v[98:101], v[152:155], v[192:195], v[98:101]
	v_mfma_f32_16x16x32_bf16 v[98:101], v[156:159], v[200:203], v[98:101]
	v_mfma_f32_16x16x32_bf16 v[82:85], v[152:155], v[204:207], v[82:85]
	v_mfma_f32_16x16x32_bf16 v[82:85], v[156:159], v[208:211], v[82:85]
	v_mfma_f32_16x16x32_bf16 v[110:113], v[160:163], v[176:179], v[110:113]
	v_mfma_f32_16x16x32_bf16 v[110:113], v[164:167], v[180:183], v[110:113]
	v_mfma_f32_16x16x32_bf16 v[94:97], v[160:163], v[184:187], v[94:97]
	v_mfma_f32_16x16x32_bf16 v[94:97], v[164:167], v[188:191], v[94:97]
	v_mfma_f32_16x16x32_bf16 v[78:81], v[160:163], v[192:195], v[78:81]
	v_mfma_f32_16x16x32_bf16 v[78:81], v[164:167], v[200:203], v[78:81]
	v_mfma_f32_16x16x32_bf16 v[70:73], v[160:163], v[204:207], v[70:73]
	v_mfma_f32_16x16x32_bf16 v[70:73], v[164:167], v[208:211], v[70:73]
	v_mfma_f32_16x16x32_bf16 v[106:109], v[168:171], v[176:179], v[106:109]
	v_mfma_f32_16x16x32_bf16 v[106:109], v[172:175], v[180:183], v[106:109]
	v_mfma_f32_16x16x32_bf16 v[90:93], v[168:171], v[184:187], v[90:93]
	v_mfma_f32_16x16x32_bf16 v[90:93], v[172:175], v[188:191], v[90:93]
	v_mfma_f32_16x16x32_bf16 v[74:77], v[168:171], v[192:195], v[74:77]
	v_mfma_f32_16x16x32_bf16 v[74:77], v[172:175], v[200:203], v[74:77]
	v_mfma_f32_16x16x32_bf16 v[66:69], v[168:171], v[204:207], v[66:69]
	v_mfma_f32_16x16x32_bf16 v[66:69], v[172:175], v[208:211], v[66:69]
	s_barrier
	s_add_u32 s98, s34, 0x80
	s_addc_u32 s99, s35, 0
	s_add_i32 s40, s54, s9
	s_mov_b32 m0, s40
	ds_read_b128 v[176:179], v143 offset:49152
	ds_read_b128 v[180:183], v143 offset:50176
	ds_read_b128 v[184:187], v143 offset:51200
	ds_read_b128 v[188:191], v143 offset:52224
	ds_read_b128 v[192:195], v143 offset:53248
	ds_read_b128 v[200:203], v143 offset:54272
	ds_read_b128 v[204:207], v143 offset:55296
	ds_read_b128 v[208:211], v143 offset:56320
	global_load_lds_dwordx4 v0, s[98:99]
	s_add_i32 m0, s40, 0x2000
	s_add_u32 s34, s34, 0x100080
	s_addc_u32 s35, s35, 0
	s_add_i32 s40, s55, s9
	global_load_lds_dwordx4 v130, s[98:99]
	s_mov_b32 m0, s40
	s_nop 0
	global_load_lds_dwordx4 v0, s[34:35]
	s_add_i32 m0, s40, 0x2000
	s_nop 0
	global_load_lds_dwordx4 v130, s[34:35]
	s_waitcnt vmcnt(6)
	s_waitcnt lgkmcnt(0)
	s_barrier
	v_mfma_f32_16x16x32_bf16 v[62:65], v[144:147], v[176:179], v[62:65]
	v_mfma_f32_16x16x32_bf16 v[62:65], v[148:151], v[180:183], v[62:65]
	v_mfma_f32_16x16x32_bf16 v[54:57], v[144:147], v[184:187], v[54:57]
	v_mfma_f32_16x16x32_bf16 v[54:57], v[148:151], v[188:191], v[54:57]
	v_mfma_f32_16x16x32_bf16 v[38:41], v[144:147], v[192:195], v[38:41]
	v_mfma_f32_16x16x32_bf16 v[38:41], v[148:151], v[200:203], v[38:41]
	v_mfma_f32_16x16x32_bf16 v[22:25], v[144:147], v[204:207], v[22:25]
	v_mfma_f32_16x16x32_bf16 v[22:25], v[148:151], v[208:211], v[22:25]
	v_mfma_f32_16x16x32_bf16 v[58:61], v[152:155], v[176:179], v[58:61]
	v_mfma_f32_16x16x32_bf16 v[58:61], v[156:159], v[180:183], v[58:61]
	v_mfma_f32_16x16x32_bf16 v[50:53], v[152:155], v[184:187], v[50:53]
	v_mfma_f32_16x16x32_bf16 v[50:53], v[156:159], v[188:191], v[50:53]
	v_mfma_f32_16x16x32_bf16 v[34:37], v[152:155], v[192:195], v[34:37]
	v_mfma_f32_16x16x32_bf16 v[34:37], v[156:159], v[200:203], v[34:37]
	v_mfma_f32_16x16x32_bf16 v[18:21], v[152:155], v[204:207], v[18:21]
	v_mfma_f32_16x16x32_bf16 v[18:21], v[156:159], v[208:211], v[18:21]
	v_mfma_f32_16x16x32_bf16 v[46:49], v[160:163], v[176:179], v[46:49]
	v_mfma_f32_16x16x32_bf16 v[46:49], v[164:167], v[180:183], v[46:49]
	v_mfma_f32_16x16x32_bf16 v[30:33], v[160:163], v[184:187], v[30:33]
	v_mfma_f32_16x16x32_bf16 v[30:33], v[164:167], v[188:191], v[30:33]
	v_mfma_f32_16x16x32_bf16 v[14:17], v[160:163], v[192:195], v[14:17]
	v_mfma_f32_16x16x32_bf16 v[14:17], v[164:167], v[200:203], v[14:17]
	v_mfma_f32_16x16x32_bf16 v[6:9], v[160:163], v[204:207], v[6:9]
	v_mfma_f32_16x16x32_bf16 v[6:9], v[164:167], v[208:211], v[6:9]
	v_mfma_f32_16x16x32_bf16 v[42:45], v[168:171], v[176:179], v[42:45]
	v_mfma_f32_16x16x32_bf16 v[42:45], v[172:175], v[180:183], v[42:45]
	v_mfma_f32_16x16x32_bf16 v[26:29], v[168:171], v[184:187], v[26:29]
	v_mfma_f32_16x16x32_bf16 v[26:29], v[172:175], v[188:191], v[26:29]
	v_mfma_f32_16x16x32_bf16 v[10:13], v[168:171], v[192:195], v[10:13]
	v_mfma_f32_16x16x32_bf16 v[10:13], v[172:175], v[200:203], v[10:13]
	v_mfma_f32_16x16x32_bf16 v[2:5], v[168:171], v[204:207], v[2:5]
	v_mfma_f32_16x16x32_bf16 v[2:5], v[172:175], v[208:211], v[2:5]
	s_barrier
	s_add_i32 s53, s53, 2
	s_add_u32 s30, s30, 0x100
	s_addc_u32 s31, s31, 0
	s_add_u32 s51, s51, 0x100
	s_addc_u32 s52, s52, 0
	s_cmp_gt_u32 s53, 61
	s_cbranch_scc0 .LBB0_801
	s_and_b64 vcc, exec, s[20:21]
	s_cbranch_vccz .LBB0_804
	s_barrier
